# hand-written dilated attention tile loop: accumulators in place (no per-tile copies), masks folded into MFMA C-init, SGPR-base loads
# speedup vs baseline: 1.0108x; 1.0108x over previous
; #define LAS __attribute__((address_space(3)))
; template <bool MASKED>
; DI void attn_tile_sw(int MODE, LAS const unsigned char* kst, LAS const unsigned char* vst, const bf16x8 (&qf)[4], float bstep, float ca, int lane, f32x16& o0, f32x16& o1, float& m, float& l) {
;     ...
;     f32x16 s; { const float sb = bstep * (float)(4 * hh - qq);
; #pragma unroll
;         for (int i = 0; i < 16; ++i) s[i] = bstep * (float)((i & 3) + 8 * (i >> 2)) + sb; }
;     {   bf16x8 kf[4];
; #pragma unroll
;         for (int st = 0; st < 4; ++st) kf[st] = *(LAS const bf16x8*)(kst + qq * 128 + (((2 * st + hh) ^ (qq & 7)) << 4));
; #pragma unroll
;         for (int st = 0; st < 4; ++st) s = MFMA32(kf[st], qf[st], s); }
;     const int q4 = (lane & 15) >> 2, p = lane & 3, blk = (lane >> 4) & 1, x = 4 * hh + q4;
;     LAS const unsigned char* vb = vst + x * 128 + 8 * (p & 1);
;     const int ch0 = ((2 * blk + (p >> 1)) ^ x) << 4, ch1 = ((4 + 2 * blk + (p >> 1)) ^ x) << 4;
;     const s16x4 va0 = vtr(vb + ch0), va1 = vtr(vb + 8 * 128 + ch0), vb0 = vtr(vb + ch1), vb1 = vtr(vb + 8 * 128 + ch1);
; DI void unit_dilated2(int u, const bf16* __restrict__ Q, const bf16* __restrict__ K, const bf16* __restrict__ V, const bf16* __restrict__ G, bf16* __restrict__ MIX, LAS unsigned char* lds, int tid, int lane, int wave) {
;     ...
;     for (int seq = 0; seq < 6; ++seq) {
;         const DilWT nw = dil_wt(seq < 5 ? seq + 1 : 5, wave, b, h, T0, qq, slope2);
;         bf16x8 qn[4];
; #pragma unroll
;         for (int st = 0; st < 4; ++st) qn[st] = *(const bf16x8*)(Q + nw.qrow * 512 + h * 64 + 16 * st + 8 * hh);
;         f32x16 o0, o1;
; #pragma unroll
;         for (int i = 0; i < 16; ++i) { o0[i] = 0.f; o1[i] = 0.f; }
;         float m = NEG, l = 0.f;
; #pragma unroll 1
;         for (int a = 4; a >= cw.a0; --a) {
;             dil_store(kst, vst, kr, vr, lane);
;             if (a > cw.a0) dil_load(kr, vr, K, V, cw.rb0 + (long)(32 * (a - 1)) * cw.gstride, cw.gstride, lane);
;             else if (seq < 5) dil_load(kr, vr, K, V, nw.rb0 + (long)(32 * 4) * nw.gstride, nw.gstride, lane);
;             const float ca = -cw.bstep * (float)(128 - 32 * a);
;             if (a == 4 || a == 0) attn_tile_sw<true>(a == 4 ? 2 : 1, kst, vst, qf, cw.bstep, ca, lane, o0, o1, m, l);
;             else attn_tile_sw<false>(0, kst, vst, qf, cw.bstep, ca, lane, o0, o1, m, l);
.LBB0_755:
	s_mov_b32 s35, s44
	s_add_i32 s44, s44, 1
	s_cmp_lg_u32 s35, 5
	s_cselect_b64 s[22:23], -1, 0
	s_and_b64 s[0:1], s[22:23], exec
	s_cselect_b32 s0, s44, 5
	s_lshl_b32 s1, s0, 3
	s_and_b32 s1, s1, 8
	s_and_b32 s0, s0, 14
	s_add_i32 s1, s1, s33
	s_sub_i32 s8, 4, s0
	s_mov_b64 s[2:3], s[16:17]
	s_lshr_b32 s16, s1, s8
	s_lshr_b32 s8, 16, s0
	s_add_i32 s8, s8, -1
	s_and_b32 s1, s1, s8
	s_lshl_b32 s9, s1, 5
	v_or_b32_e32 v3, s9, v228
	v_lshlrev_b32_e32 v3, s0, v3
	v_mov_b32_e32 v241, v184
	v_add_u32_e32 v184, s16, v3
	v_ashrrev_i32_e32 v185, 31, v184
	v_lshl_add_u64 v[4:5], s[10:11], 0, v[184:185]
	v_lshlrev_b64 v[4:5], 10, v[4:5]
	s_waitcnt vmcnt(0)
	v_mov_b64_e32 v[164:165], v[132:133]
	v_mov_b64_e32 v[168:169], v[124:125]
	v_mov_b64_e32 v[172:173], v[120:121]
	v_mov_b64_e32 v[176:177], v[116:117]
	v_lshl_add_u64 v[4:5], v[196:197], 0, v[4:5]
	v_mov_b64_e32 v[162:163], v[130:131]
	v_mov_b64_e32 v[166:167], v[122:123]
	v_mov_b64_e32 v[170:171], v[118:119]
	v_mov_b64_e32 v[174:175], v[114:115]
	global_load_dwordx4 v[114:117], v[4:5], off
	global_load_dwordx4 v[118:121], v[4:5], off offset:32
	global_load_dwordx4 v[122:125], v[4:5], off offset:64
	global_load_dwordx4 v[130:133], v[4:5], off offset:96
	s_lshr_b32 s8, s34, s0
	s_add_i32 s1, s9, s8
	s_add_i32 s8, s1, 0xffffff80
	s_ashr_i32 s9, s8, 31
	s_lshl_b32 s38, 0x200, s0
	s_lshl_b64 s[8:9], s[8:9], s0
	s_add_u32 s16, s12, s16
	s_addc_u32 s17, s13, 0
	s_add_u32 s8, s16, s8
	s_addc_u32 s9, s17, s9
	s_lshl_b64 s[8:9], s[8:9], 9
	s_or_b64 s[16:17], s[8:9], s[14:15]
	s_mov_b64 s[20:21], s[18:19]
	s_mov_b64 s[18:19], s[38:39]
	v_mov_b32_e32 v5, s17
	v_or_b32_e32 v4, s16, v188
	s_lshl_b32 s38, s38, 7
	s_add_i32 s8, s0, 9
	v_lshl_add_u64 v[4:5], v[4:5], 0, s[38:39]
	v_lshlrev_b64 v[6:7], s8, v[186:187]
	v_lshl_add_u64 v[6:7], v[4:5], 0, v[6:7]
	v_lshlrev_b64 v[6:7], 1, v[6:7]
	v_lshl_add_u64 v[200:201], s[76:77], 0, v[6:7]
	v_lshl_add_u64 v[202:203], s[80:81], 0, v[6:7]
	v_lshlrev_b64 v[6:7], s8, v[190:191]
	v_lshl_add_u64 v[6:7], v[4:5], 0, v[6:7]
	v_lshlrev_b64 v[6:7], 1, v[6:7]
	v_lshl_add_u64 v[204:205], s[76:77], 0, v[6:7]
	v_lshl_add_u64 v[206:207], s[80:81], 0, v[6:7]
	v_lshlrev_b64 v[6:7], s8, v[192:193]
	v_lshl_add_u64 v[6:7], v[4:5], 0, v[6:7]
	v_lshlrev_b64 v[6:7], 1, v[6:7]
	v_lshl_add_u64 v[208:209], s[76:77], 0, v[6:7]
	v_lshl_add_u64 v[210:211], s[80:81], 0, v[6:7]
	v_lshlrev_b64 v[6:7], s8, v[194:195]
	v_lshl_add_u64 v[4:5], v[4:5], 0, v[6:7]
	v_lshlrev_b64 v[4:5], 1, v[4:5]
	v_lshl_add_u64 v[212:213], s[76:77], 0, v[4:5]
	v_lshl_add_u64 v[214:215], s[80:81], 0, v[4:5]
	v_mul_lo_u32 v216, s20, v186
	s_mul_i32 s8, s20, 0x60
	s_add_u32 s8, s2, s8
	s_addc_u32 s9, s3, 0
	s_lshl_b64 s[8:9], s[8:9], 1
	s_add_u32 s8, s8, s76
	s_addc_u32 s9, s9, s77
	s_sub_u32 s3, s80, s76
	s_lshl_b32 s2, s20, 4
	v_add_lshl_u32 v216, v216, v188, 1
	v_add_u32_e32 v217, s2, v216
	v_add_u32_e32 v218, s2, v217
	v_add_u32_e32 v219, s2, v218
	v_add_u32_e32 v220, s3, v216
	v_add_u32_e32 v221, s3, v217
	v_add_u32_e32 v222, s3, v218
	v_add_u32_e32 v223, s3, v219
	v_mul_f32_e32 v4, v199, v231
	v_mul_f32_e32 v198, 0, v199
	v_mov_b32_e32 v6, v199
	v_mov_b32_e32 v16, v2
	v_mov_b32_e32 v17, v2
	v_pk_add_f32 v[18:19], v[198:199], v[4:5] op_sel_hi:[1,0]
	v_pk_fma_f32 v[20:21], v[6:7], s[96:97], v[4:5] op_sel_hi:[0,1,0]
	v_pk_fma_f32 v[22:23], v[6:7], s[74:75], v[4:5] op_sel_hi:[0,1,0]
	v_pk_fma_f32 v[24:25], v[6:7], s[82:83], v[4:5] op_sel_hi:[0,1,0]
	v_pk_fma_f32 v[26:27], v[6:7], s[86:87], v[4:5] op_sel_hi:[0,1,0]
	v_pk_fma_f32 v[28:29], v[6:7], s[90:91], v[4:5] op_sel_hi:[0,1,0]
	v_pk_fma_f32 v[30:31], v[6:7], s[68:69], v[4:5] op_sel_hi:[0,1,0]
	v_pk_fma_f32 v[32:33], v[6:7], s[70:71], v[4:5] op_sel_hi:[0,1,0]
	v_cmp_le_i32_e32 vcc, 0, v232
	v_cmp_ge_i32_e64 s[26:27], 0, v232
	v_cmp_le_i32_e64 s[2:3], 1, v232
	v_cndmask_b32_e32 v34, v226, v18, vcc
	v_cmp_ge_i32_e32 vcc, 1, v232
	v_cndmask_b32_e64 v50, v226, v18, s[26:27]
	v_cmp_le_i32_e64 s[26:27], 2, v232
	v_cndmask_b32_e64 v35, v226, v19, s[2:3]
	v_cmp_ge_i32_e64 s[2:3], 2, v232
	v_cndmask_b32_e32 v51, v226, v19, vcc
	v_cmp_le_i32_e32 vcc, 3, v232
	v_cndmask_b32_e64 v36, v226, v20, s[26:27]
	v_cmp_ge_i32_e64 s[26:27], 3, v232
	v_cndmask_b32_e64 v52, v226, v20, s[2:3]
	v_cmp_le_i32_e64 s[2:3], 8, v232
	v_cndmask_b32_e32 v37, v226, v21, vcc
	v_cmp_ge_i32_e32 vcc, 8, v232
	v_cndmask_b32_e64 v53, v226, v21, s[26:27]
	v_cmp_le_i32_e64 s[26:27], 9, v232
	v_cndmask_b32_e64 v38, v226, v22, s[2:3]
	v_cmp_ge_i32_e64 s[2:3], 9, v232
	v_cndmask_b32_e32 v54, v226, v22, vcc
	v_cmp_le_i32_e32 vcc, 10, v232
	v_cndmask_b32_e64 v39, v226, v23, s[26:27]
	v_cmp_ge_i32_e64 s[26:27], 10, v232
	v_cndmask_b32_e64 v55, v226, v23, s[2:3]
	v_cmp_le_i32_e64 s[2:3], 11, v232
	v_cndmask_b32_e32 v40, v226, v24, vcc
	v_cmp_ge_i32_e32 vcc, 11, v232
	v_cndmask_b32_e64 v56, v226, v24, s[26:27]
	v_cmp_le_i32_e64 s[26:27], 16, v232
	v_cndmask_b32_e64 v41, v226, v25, s[2:3]
	v_cmp_ge_i32_e64 s[2:3], 16, v232
	v_cndmask_b32_e32 v57, v226, v25, vcc
	v_cmp_le_i32_e32 vcc, 17, v232
	v_cndmask_b32_e64 v42, v226, v26, s[26:27]
	v_cmp_ge_i32_e64 s[26:27], 17, v232
	v_cndmask_b32_e64 v58, v226, v26, s[2:3]
	v_cmp_le_i32_e64 s[2:3], 18, v232
	v_cndmask_b32_e32 v43, v226, v27, vcc
	v_cmp_ge_i32_e32 vcc, 18, v232
	v_cndmask_b32_e64 v59, v226, v27, s[26:27]
	v_cmp_le_i32_e64 s[26:27], 19, v232
	v_cndmask_b32_e64 v44, v226, v28, s[2:3]
	v_cmp_ge_i32_e64 s[2:3], 19, v232
	v_cndmask_b32_e32 v60, v226, v28, vcc
	v_cmp_le_i32_e32 vcc, 24, v232
	v_cndmask_b32_e64 v45, v226, v29, s[26:27]
	v_cmp_ge_i32_e64 s[26:27], 24, v232
	v_cndmask_b32_e64 v61, v226, v29, s[2:3]
	v_cmp_le_i32_e64 s[2:3], 25, v232
	v_cndmask_b32_e32 v46, v226, v30, vcc
	v_cmp_ge_i32_e32 vcc, 25, v232
	v_cndmask_b32_e64 v62, v226, v30, s[26:27]
	v_cmp_le_i32_e64 s[26:27], 26, v232
	v_cndmask_b32_e64 v47, v226, v31, s[2:3]
	v_cmp_ge_i32_e64 s[2:3], 26, v232
	v_cndmask_b32_e32 v63, v226, v31, vcc
	v_cmp_le_i32_e32 vcc, 27, v232
	v_cndmask_b32_e64 v48, v226, v32, s[26:27]
	v_cmp_ge_i32_e64 s[26:27], 27, v232
	v_cndmask_b32_e64 v64, v226, v32, s[2:3]
	v_cndmask_b32_e32 v49, v226, v33, vcc
	v_cndmask_b32_e64 v65, v226, v33, s[26:27]
	v_mov_b32_e32 v66, 0
	v_mov_b32_e32 v67, 0
	v_mov_b32_e32 v68, 0
	v_mov_b32_e32 v69, 0
	v_mov_b32_e32 v70, 0
	v_mov_b32_e32 v71, 0
	v_mov_b32_e32 v72, 0
	v_mov_b32_e32 v73, 0
	v_mov_b32_e32 v74, 0
	v_mov_b32_e32 v75, 0
	v_mov_b32_e32 v76, 0
	v_mov_b32_e32 v77, 0
	v_mov_b32_e32 v78, 0
	v_mov_b32_e32 v79, 0
	v_mov_b32_e32 v80, 0
	v_mov_b32_e32 v81, 0
	v_mov_b32_e32 v82, 0
	v_mov_b32_e32 v83, 0
	v_mov_b32_e32 v84, 0
	v_mov_b32_e32 v85, 0
	v_mov_b32_e32 v86, 0
	v_mov_b32_e32 v87, 0
	v_mov_b32_e32 v88, 0
	v_mov_b32_e32 v89, 0
	v_mov_b32_e32 v90, 0
	v_mov_b32_e32 v91, 0
	v_mov_b32_e32 v92, 0
	v_mov_b32_e32 v93, 0
	v_mov_b32_e32 v94, 0
	v_mov_b32_e32 v95, 0
	v_mov_b32_e32 v96, 0
	v_mov_b32_e32 v97, 0
	s_lshl_b32 s2, s20, 6
	s_mov_b32 s31, 4
	s_mov_b32 s51, 0
	v_mov_b32_e32 v198, 0xf149f2ca
	v_mov_b32_e32 v185, 0
; #define LAS __attribute__((address_space(3)))
; template <bool MASKED>
; DI void attn_tile_sw(int MODE, LAS const unsigned char* kst, LAS const unsigned char* vst, const bf16x8 (&qf)[4], float bstep, float ca, int lane, f32x16& o0, f32x16& o1, float& m, float& l) {
;     const int qq = lane & 31, hh = lane >> 5;
;     f32x16 s; { const float sb = bstep * (float)(4 * hh - qq);
; #pragma unroll
;         for (int i = 0; i < 16; ++i) s[i] = bstep * (float)((i & 3) + 8 * (i >> 2)) + sb; }
;     {   bf16x8 kf[4];
; #pragma unroll
;         for (int st = 0; st < 4; ++st) kf[st] = *(LAS const bf16x8*)(kst + qq * 128 + (((2 * st + hh) ^ (qq & 7)) << 4));
; #pragma unroll
;         for (int st = 0; st < 4; ++st) s = MFMA32(kf[st], qf[st], s); }
;     const int q4 = (lane & 15) >> 2, p = lane & 3, blk = (lane >> 4) & 1, x = 4 * hh + q4;
;     LAS const unsigned char* vb = vst + x * 128 + 8 * (p & 1);
;     const int ch0 = ((2 * blk + (p >> 1)) ^ x) << 4, ch1 = ((4 + 2 * blk + (p >> 1)) ^ x) << 4;
;     const s16x4 va0 = vtr(vb + ch0), va1 = vtr(vb + 8 * 128 + ch0), vb0 = vtr(vb + ch1), vb1 = vtr(vb + 8 * 128 + ch1);
;     const s16x4 vc0 = vtr(vb + 16 * 128 + ch0), vc1 = vtr(vb + 24 * 128 + ch0), vd0 = vtr(vb + 16 * 128 + ch1), vd1 = vtr(vb + 24 * 128 + ch1);
;     if (MASKED) { const int dq = (MODE == 1) ? (qq - 4 * hh) : (4 * hh - qq);
; #pragma unroll
;         for (int r = 0; r < 16; ++r) { const int kq = (r & 3) + 8 * (r >> 2); s[r] = (((MODE == 1) ? kq : -kq) < dq) ? NEG : s[r]; } }
;     float tmax = vmax3(s[0], s[1], s[2]);
;     tmax = vmax3(tmax, s[3], s[4]); tmax = vmax3(tmax, s[5], s[6]); tmax = vmax3(tmax, s[7], s[8]); tmax = vmax3(tmax, s[9], s[10]);
;     tmax = vmax3(tmax, s[11], s[12]); tmax = vmax3(tmax, s[13], s[14]); tmax = fmaxf(tmax, s[15]);
;     tmax = half_max(tmax);
;     const float mn = fmaxf(m, tmax + ca), mrel = mn - ca;
;     if (__builtin_amdgcn_ballot_w64(mn > m) != 0ull) { const float alpha = fexp2(m - mn); l *= alpha;
; #pragma unroll
;         for (int i = 0; i < 16; ++i) { o0[i] *= alpha; o1[i] *= alpha; } }
;     m = mn;
;     float ps = 0.f;
; #pragma unroll
;     for (int r = 0; r < 16; ++r) { s[r] = fexp2(s[r] - mrel); ps += s[r]; }
;     l += half_sum(ps);
;     v4u pa, pb;
;     pa.x = cvtpk(s[0], s[1]); pa.y = cvtpk(s[2], s[3]); pa.z = cvtpk(s[4], s[5]); pa.w = cvtpk(s[6], s[7]);
.Ldil_top:
	s_waitcnt vmcnt(7)
	ds_write_b128 v234, v[126:129]
	s_waitcnt vmcnt(6)
	ds_write_b128 v234, v[134:137] offset:4096
	s_waitcnt vmcnt(5)
	ds_write_b128 v234, v[138:141] offset:1024
	s_waitcnt vmcnt(4)
	ds_write_b128 v234, v[142:145] offset:5120
	s_waitcnt vmcnt(3)
	ds_write_b128 v234, v[146:149] offset:2048
	s_waitcnt vmcnt(2)
	ds_write_b128 v234, v[150:153] offset:6144
	s_waitcnt vmcnt(1)
	ds_write_b128 v234, v[154:157] offset:3072
	s_waitcnt vmcnt(0)
	ds_write_b128 v234, v[158:161] offset:7168
	s_cmp_le_i32 s31, s47
	s_cbranch_scc1 .Ldil_ld_nextwt
	global_load_dwordx4 v[126:129], v216, s[8:9]
	global_load_dwordx4 v[134:137], v220, s[8:9]
	global_load_dwordx4 v[138:141], v217, s[8:9]
	global_load_dwordx4 v[142:145], v221, s[8:9]
	global_load_dwordx4 v[146:149], v218, s[8:9]
	global_load_dwordx4 v[150:153], v222, s[8:9]
	global_load_dwordx4 v[154:157], v219, s[8:9]
	global_load_dwordx4 v[158:161], v223, s[8:9]
	s_sub_u32 s8, s8, s2
	s_subb_u32 s9, s9, 0
	s_branch .Ldil_ld_done
.Ldil_ld_nextwt:
	s_andn2_b64 vcc, exec, s[22:23]
	s_cbranch_vccnz .Ldil_ld_done
	global_load_dwordx4 v[126:129], v[200:201], off
	global_load_dwordx4 v[134:137], v[202:203], off
	global_load_dwordx4 v[138:141], v[204:205], off
	global_load_dwordx4 v[142:145], v[206:207], off
	global_load_dwordx4 v[146:149], v[208:209], off
	global_load_dwordx4 v[150:153], v[210:211], off
	global_load_dwordx4 v[154:157], v[212:213], off
	global_load_dwordx4 v[158:161], v[214:215], off
.Ldil_ld_done:
	ds_read_b128 v[4:7], v235
	ds_read_b128 v[8:11], v236
	s_cmp_eq_u32 s31, 4
	s_cbranch_scc1 .Ldil_qk_m2
	s_cmp_eq_u32 s31, 0
	s_cbranch_scc1 .Ldil_qk_m1
	s_waitcnt lgkmcnt(1)
	v_mfma_f32_32x32x16_bf16 v[98:113], v[4:7], v[174:177], v[18:33]
	s_branch .Ldil_qk_join
.Ldil_qk_m2:
	s_waitcnt lgkmcnt(1)
	v_mfma_f32_32x32x16_bf16 v[98:113], v[4:7], v[174:177], v[34:49]
	s_branch .Ldil_qk_join
.Ldil_qk_m1:
	s_waitcnt lgkmcnt(1)
	v_mfma_f32_32x32x16_bf16 v[98:113], v[4:7], v[174:177], v[50:65]
.Ldil_qk_join:
	ds_read_b128 v[4:7], v237
	ds_read_b128 v[12:15], v238
	s_waitcnt lgkmcnt(2)
	v_mfma_f32_32x32x16_bf16 v[98:113], v[8:11], v[170:173], v[98:113]
	ds_read_b64_tr_b16 v[178:179], v239 offset:4096
	ds_read_b64_tr_b16 v[180:181], v239 offset:5120
	ds_read_b64_tr_b16 v[8:9], v239 offset:6144
	ds_read_b64_tr_b16 v[10:11], v239 offset:7168
	s_waitcnt lgkmcnt(5)
	v_mfma_f32_32x32x16_bf16 v[98:113], v[4:7], v[166:169], v[98:113]
	s_waitcnt lgkmcnt(4)
	v_mfma_f32_32x32x16_bf16 v[98:113], v[12:15], v[162:165], v[98:113]
	ds_read_b64_tr_b16 v[12:13], v240 offset:4096
	ds_read_b64_tr_b16 v[14:15], v240 offset:5120
	ds_read_b64_tr_b16 v[4:5], v240 offset:6144
	ds_read_b64_tr_b16 v[6:7], v240 offset:7168
	v_cvt_f32_i32_e32 v3, s51
	s_cmp_le_i32 s31, s47
	s_cselect_b64 s[26:27], -1, 0
	v_mul_f32_e64 v3, -v199, v3
	s_add_i32 s51, s51, 32
	s_add_i32 s31, s31, -1
	s_nop 1
	v_max3_f32 v17, v98, v99, v100
	v_max3_f32 v16, v101, v102, v103
	v_max3_f32 v17, v17, v104, v105
	v_max3_f32 v16, v16, v106, v107
	v_max3_f32 v17, v17, v108, v109
	v_max3_f32 v16, v16, v110, v111
	v_max3_f32 v17, v17, v112, v113
	v_max_f32_e32 v17, v17, v16
	v_mov_b32_e32 v16, v17
	s_nop 1
	v_permlane32_swap_b32_e32 v17, v16
	v_max_f32_e32 v17, v17, v16
	v_add_f32_e32 v17, v3, v17
	v_max_f32_e32 v17, v198, v17
	v_cmp_gt_f32_e32 vcc, v17, v198
	s_cbranch_vccz .Ldil_norescale
	v_sub_f32_e32 v16, v198, v17
	v_exp_f32_e32 v16, v16
	s_nop 0
	v_mul_f32_e32 v185, v185, v16
	v_pk_mul_f32 v[66:67], v[66:67], v[16:17] op_sel_hi:[1,0]
	v_pk_mul_f32 v[68:69], v[68:69], v[16:17] op_sel_hi:[1,0]
	v_pk_mul_f32 v[70:71], v[70:71], v[16:17] op_sel_hi:[1,0]
	v_pk_mul_f32 v[72:73], v[72:73], v[16:17] op_sel_hi:[1,0]
	v_pk_mul_f32 v[74:75], v[74:75], v[16:17] op_sel_hi:[1,0]
	v_pk_mul_f32 v[76:77], v[76:77], v[16:17] op_sel_hi:[1,0]
	v_pk_mul_f32 v[78:79], v[78:79], v[16:17] op_sel_hi:[1,0]
	v_pk_mul_f32 v[80:81], v[80:81], v[16:17] op_sel_hi:[1,0]
	v_pk_mul_f32 v[82:83], v[82:83], v[16:17] op_sel_hi:[1,0]
	v_pk_mul_f32 v[84:85], v[84:85], v[16:17] op_sel_hi:[1,0]
	v_pk_mul_f32 v[86:87], v[86:87], v[16:17] op_sel_hi:[1,0]
	v_pk_mul_f32 v[88:89], v[88:89], v[16:17] op_sel_hi:[1,0]
	v_pk_mul_f32 v[90:91], v[90:91], v[16:17] op_sel_hi:[1,0]
	v_pk_mul_f32 v[92:93], v[92:93], v[16:17] op_sel_hi:[1,0]
	v_pk_mul_f32 v[94:95], v[94:95], v[16:17] op_sel_hi:[1,0]
	v_pk_mul_f32 v[96:97], v[96:97], v[16:17] op_sel_hi:[1,0]
.Ldil_norescale:
	v_sub_f32_e32 v243, v17, v3
	v_mov_b32_e32 v198, v17
	v_sub_f32_e32 v98, v98, v243
	v_exp_f32_e32 v244, v98
	v_sub_f32_e32 v99, v99, v243
	v_exp_f32_e32 v99, v99
	v_sub_f32_e32 v100, v100, v243
	v_exp_f32_e32 v245, v100
	v_sub_f32_e32 v100, v101, v243
	v_exp_f32_e32 v101, v100
	v_sub_f32_e32 v100, v102, v243
	v_add_f32_e32 v98, 0, v244
	v_exp_f32_e32 v102, v100
	v_sub_f32_e32 v100, v103, v243
	v_add_f32_e32 v98, v99, v98
	v_exp_f32_e32 v103, v100
	v_sub_f32_e32 v100, v104, v243
	v_add_f32_e32 v98, v245, v98
	v_exp_f32_e32 v104, v100
	v_sub_f32_e32 v100, v105, v243
	v_add_f32_e32 v98, v101, v98
	v_exp_f32_e32 v105, v100
	v_sub_f32_e32 v100, v106, v243
	v_add_f32_e32 v98, v102, v98
	v_exp_f32_e32 v106, v100
	v_sub_f32_e32 v100, v107, v243
	v_add_f32_e32 v98, v103, v98
	v_exp_f32_e32 v107, v100
	v_sub_f32_e32 v100, v108, v243
	v_add_f32_e32 v98, v104, v98
	v_exp_f32_e32 v108, v100
	v_sub_f32_e32 v100, v109, v243
	v_add_f32_e32 v98, v105, v98
	v_exp_f32_e32 v109, v100
	v_sub_f32_e32 v100, v110, v243
	v_add_f32_e32 v98, v106, v98
	v_exp_f32_e32 v110, v100
	v_sub_f32_e32 v100, v111, v243
	v_add_f32_e32 v98, v107, v98
	v_exp_f32_e32 v111, v100
	v_sub_f32_e32 v100, v112, v243
	v_add_f32_e32 v98, v108, v98
	v_exp_f32_e32 v112, v100
	v_sub_f32_e32 v100, v113, v243
	v_add_f32_e32 v98, v109, v98
	v_exp_f32_e32 v113, v100
	v_add_f32_e32 v98, v110, v98
	v_add_f32_e32 v98, v111, v98
	v_add_f32_e32 v98, v112, v98
	v_add_f32_e32 v98, v113, v98
	v_mov_b32_e32 v100, v98
	s_nop 1
	v_permlane32_swap_b32_e32 v98, v100
	v_add_f32_e32 v98, v98, v100
	v_cvt_pk_bf16_f32 v100, v244, v99
	v_cvt_pk_bf16_f32 v101, v245, v101
	v_cvt_pk_bf16_f32 v102, v102, v103
	v_cvt_pk_bf16_f32 v103, v104, v105
	v_cvt_pk_bf16_f32 v104, v106, v107
	v_cvt_pk_bf16_f32 v105, v108, v109
	s_waitcnt lgkmcnt(6)
	v_mfma_f32_32x32x16_bf16 v[66:81], v[178:181], v[100:103], v[66:81]
	v_cvt_pk_bf16_f32 v106, v110, v111
	v_cvt_pk_bf16_f32 v107, v112, v113
	v_add_f32_e32 v185, v185, v98
	s_waitcnt lgkmcnt(2)
	v_mfma_f32_32x32x16_bf16 v[82:97], v[12:15], v[100:103], v[82:97]
	v_mfma_f32_32x32x16_bf16 v[66:81], v[8:11], v[104:107], v[66:81]
	s_waitcnt lgkmcnt(0)
	v_mfma_f32_32x32x16_bf16 v[82:97], v[4:7], v[104:107], v[82:97]
	s_and_b64 vcc, exec, s[26:27]
	s_cbranch_vccz .Ldil_top
	v_mov_b32_e32 v98, v185
	v_mov_b32_e32 v17, v198
